# hazard fix: one extra wait state between the last bf16 pack of P and the PV MFMA that reads it in the diff loop's second half-step (VALU write -> MFMA read needs 2 wait states; was 1)
# baseline (speedup 1.0000x reference)
.Ld_goB:
	s_setprio 1
	s_waitcnt lgkmcnt(11)
	v_mfma_f32_32x32x16_bf16 v[98:113], v[226:229], v[114:117], v[66:81]
	v_exp_f32_e32 v82, v82
	v_exp_f32_e32 v83, v83
	s_waitcnt lgkmcnt(10)
	v_mfma_f32_32x32x16_bf16 v[98:113], v[230:233], v[118:121], v[98:113]
	v_exp_f32_e32 v84, v84
	v_exp_f32_e32 v85, v85
	v_cvt_pk_bf16_f32 v214, v82, v83
	s_waitcnt lgkmcnt(9)
	v_mfma_f32_32x32x16_bf16 v[98:113], v[234:237], v[122:125], v[98:113]
	v_exp_f32_e32 v86, v86
	v_exp_f32_e32 v87, v87
	v_cvt_pk_bf16_f32 v215, v84, v85
	s_waitcnt lgkmcnt(8)
	v_mfma_f32_32x32x16_bf16 v[98:113], v[238:241], v[126:129], v[98:113]
	v_exp_f32_e32 v88, v88
	v_exp_f32_e32 v89, v89
	v_cvt_pk_bf16_f32 v216, v86, v87
	v_cvt_pk_bf16_f32 v217, v88, v89
	ds_read_b64_tr_b16 v[226:227], v213 offset:24576
	ds_read_b64_tr_b16 v[230:231], v213 offset:24640
	ds_read_b64_tr_b16 v[234:235], v213 offset:24704
	ds_read_b64_tr_b16 v[238:239], v213 offset:24768
	ds_read_b64_tr_b16 v[228:229], v213 offset:27136
	ds_read_b64_tr_b16 v[232:233], v213 offset:27200
	ds_read_b64_tr_b16 v[236:237], v213 offset:27264
	ds_read_b64_tr_b16 v[240:241], v213 offset:27328
	s_waitcnt lgkmcnt(11)
	v_mfma_f32_32x32x16_bf16 v[50:65], v[142:145], v[214:217], v[50:65]
	v_exp_f32_e32 v90, v90
	v_exp_f32_e32 v91, v91
	v_add_f32_e32 v248, v82, v84
	s_waitcnt lgkmcnt(10)
	v_mfma_f32_32x32x16_bf16 v[34:49], v[146:149], v[214:217], v[34:49]
	v_exp_f32_e32 v92, v92
	v_exp_f32_e32 v93, v93
	v_cvt_pk_bf16_f32 v218, v90, v91
	v_add_f32_e32 v249, v83, v85
	s_waitcnt lgkmcnt(9)
	v_mfma_f32_32x32x16_bf16 v[18:33], v[150:153], v[214:217], v[18:33]
	v_exp_f32_e32 v94, v94
	v_exp_f32_e32 v95, v95
	v_cvt_pk_bf16_f32 v219, v92, v93
	v_add_f32_e32 v248, v248, v86
	s_waitcnt lgkmcnt(8)
	v_mfma_f32_32x32x16_bf16 v[2:17], v[154:157], v[214:217], v[2:17]
	v_exp_f32_e32 v96, v96
	v_exp_f32_e32 v97, v97
	v_cvt_pk_bf16_f32 v220, v94, v95
	v_cvt_pk_bf16_f32 v221, v96, v97
	s_nop 0
	s_waitcnt lgkmcnt(3)
	v_mfma_f32_32x32x16_bf16 v[50:65], v[226:229], v[218:221], v[50:65]
	v_max3_f32 v223, v98, v99, v100
	v_max3_f32 v224, v101, v102, v103
	v_add_f32_e32 v249, v249, v87
	v_add_f32_e32 v248, v248, v88
	v_add_f32_e32 v249, v249, v89
	s_waitcnt lgkmcnt(2)
	v_mfma_f32_32x32x16_bf16 v[34:49], v[230:233], v[218:221], v[34:49]
	v_max3_f32 v223, v223, v104, v105
	v_max3_f32 v224, v224, v106, v107
	v_add_f32_e32 v248, v248, v90
	v_add_f32_e32 v249, v249, v91
	v_add_f32_e32 v248, v248, v92
	s_waitcnt lgkmcnt(1)
	v_mfma_f32_32x32x16_bf16 v[18:33], v[234:237], v[218:221], v[18:33]
	v_max3_f32 v223, v223, v108, v109
	v_max3_f32 v224, v224, v110, v111
	v_add_f32_e32 v249, v249, v93
	v_add_f32_e32 v248, v248, v94
	v_add_f32_e32 v249, v249, v95
	s_waitcnt lgkmcnt(0)
	v_mfma_f32_32x32x16_bf16 v[2:17], v[238:241], v[218:221], v[2:17]
	s_setprio 0
	v_max3_f32 v223, v223, v112, v113
	v_max_f32_e32 v223, v223, v224
	v_cmp_lt_f32_e32 vcc, s61, v223
	v_add_f32_e32 v248, v248, v96
	v_add_f32_e32 v249, v249, v97
	v_add_f32_e32 v248, v248, v249
	v_add_f32_e32 v0, v0, v248
	s_cmp_eq_u32 s10, 0x17a0000
	s_cbranch_scc1 .Ld_next
	s_xor_b32 s12, s30, 1
	s_mulk_i32 s12, 0x7400
	v_add3_u32 v246, s12, v206, v183
	s_waitcnt vmcnt(2)
	ds_write_b128 v246, v[130:133]
	v_add3_u32 v246, s12, v205, v207
	s_cmp_gt_u32 s29, 61
	s_waitcnt vmcnt(1)
	ds_write_b128 v246, v[134:137] offset:9216
	s_waitcnt vmcnt(0)
	ds_write_b128 v246, v[138:141] offset:19456
	s_cbranch_scc1 .Ld_next
	v_lshl_add_u64 v[130:131], v[188:189], 0, s[10:11]
	v_lshl_add_u64 v[134:135], v[190:191], 0, s[10:11]
	v_lshl_add_u64 v[138:139], v[192:193], 0, s[10:11]
	global_load_dwordx4 v[130:133], v[130:131], off
	s_nop 0
	global_load_dwordx4 v[134:137], v[134:135], off
	s_nop 0
	global_load_dwordx4 v[138:141], v[138:139], off
